# up-projection K-loop: LDS-DMA in scalar-base + 32-bit offset form (no 64-bit VALU address adds)
# baseline (speedup 1.0000x reference)
.LBB0_363:
	s_add_u32 s34, s30, 0xfffc0080
	s_addc_u32 s35, s31, -1
	s_add_i32 s57, 0, 0x10000
	s_cmp_eq_u32 s56, 12
	s_cselect_b32 s37, s23, s35
	s_cselect_b32 s36, s39, s34
	v_add_u32_e32 v146, s57, v155
	s_cselect_b32 s35, s21, s43
	s_cselect_b32 s34, s40, s41
	s_add_i32 s60, 0, 0x14000
	ds_read_b128 v[142:145], v146
	ds_read_b128 v[168:171], v146 offset:1024
	ds_read_b128 v[172:175], v146 offset:2048
	ds_read_b128 v[176:179], v146 offset:3072
	v_add_u32_e32 v146, s60, v155
	ds_read_b128 v[180:183], v146
	ds_read_b128 v[184:187], v146 offset:1024
	ds_read_b128 v[188:191], v146 offset:2048
	ds_read_b128 v[192:195], v146 offset:3072
	s_add_i32 m0, s48, 0xc000
	ds_read_b128 v[196:199], v157
	ds_read_b128 v[200:203], v157 offset:1024
	ds_read_b128 v[204:207], v157 offset:2048
	ds_read_b128 v[220:223], v157 offset:3072
	ds_read_b128 v[236:239], v157 offset:4096
	ds_read_b128 v[240:243], v157 offset:5120
	ds_read_b128 v[244:247], v157 offset:6144
	ds_read_b128 v[248:251], v157 offset:7168
	global_load_lds_dwordx4 v140, s[30:31]
	s_add_i32 m0, s48, 0xe000
	s_nop 0
	global_load_lds_dwordx4 v138, s[30:31]
	s_waitcnt vmcnt(8)
	s_waitcnt lgkmcnt(0)
	s_barrier
	s_waitcnt lgkmcnt(0)
	v_mfma_f32_16x16x32_bf16 v[126:129], v[142:145], v[196:199], v[126:129]
	v_mfma_f32_16x16x32_bf16 v[118:121], v[172:175], v[196:199], v[118:121]
	v_mfma_f32_16x16x32_bf16 v[110:113], v[142:145], v[204:207], v[110:113]
	v_mfma_f32_16x16x32_bf16 v[102:105], v[172:175], v[204:207], v[102:105]
	v_mfma_f32_16x16x32_bf16 v[94:97], v[142:145], v[236:239], v[94:97]
	v_mfma_f32_16x16x32_bf16 v[86:89], v[172:175], v[236:239], v[86:89]
	v_mfma_f32_16x16x32_bf16 v[78:81], v[142:145], v[244:247], v[78:81]
	v_mfma_f32_16x16x32_bf16 v[70:73], v[172:175], v[244:247], v[70:73]
	v_mfma_f32_16x16x32_bf16 v[126:129], v[168:171], v[200:203], v[126:129]
	v_mfma_f32_16x16x32_bf16 v[118:121], v[176:179], v[200:203], v[118:121]
	v_mfma_f32_16x16x32_bf16 v[110:113], v[168:171], v[220:223], v[110:113]
	v_mfma_f32_16x16x32_bf16 v[102:105], v[176:179], v[220:223], v[102:105]
	v_mfma_f32_16x16x32_bf16 v[94:97], v[168:171], v[240:243], v[94:97]
	v_mfma_f32_16x16x32_bf16 v[86:89], v[176:179], v[240:243], v[86:89]
	v_mfma_f32_16x16x32_bf16 v[78:81], v[168:171], v[248:251], v[78:81]
	v_mfma_f32_16x16x32_bf16 v[70:73], v[176:179], v[248:251], v[70:73]
	v_mfma_f32_16x16x32_bf16 v[122:125], v[180:183], v[196:199], v[122:125]
	v_mfma_f32_16x16x32_bf16 v[114:117], v[188:191], v[196:199], v[114:117]
	v_mfma_f32_16x16x32_bf16 v[106:109], v[180:183], v[204:207], v[106:109]
	v_mfma_f32_16x16x32_bf16 v[98:101], v[188:191], v[204:207], v[98:101]
	v_mfma_f32_16x16x32_bf16 v[90:93], v[180:183], v[236:239], v[90:93]
	v_mfma_f32_16x16x32_bf16 v[82:85], v[188:191], v[236:239], v[82:85]
	v_mfma_f32_16x16x32_bf16 v[74:77], v[180:183], v[244:247], v[74:77]
	v_mfma_f32_16x16x32_bf16 v[66:69], v[188:191], v[244:247], v[66:69]
	v_mfma_f32_16x16x32_bf16 v[122:125], v[184:187], v[200:203], v[122:125]
	v_mfma_f32_16x16x32_bf16 v[114:117], v[192:195], v[200:203], v[114:117]
	v_mfma_f32_16x16x32_bf16 v[106:109], v[184:187], v[220:223], v[106:109]
	v_mfma_f32_16x16x32_bf16 v[98:101], v[192:195], v[220:223], v[98:101]
	v_mfma_f32_16x16x32_bf16 v[90:93], v[184:187], v[240:243], v[90:93]
	v_mfma_f32_16x16x32_bf16 v[82:85], v[192:195], v[240:243], v[82:85]
	v_mfma_f32_16x16x32_bf16 v[74:77], v[184:187], v[248:251], v[74:77]
	v_mfma_f32_16x16x32_bf16 v[66:69], v[192:195], v[248:251], v[66:69]
	s_barrier
	s_add_i32 s57, s57, s44
	s_mov_b32 m0, s57
	ds_read_b128 v[196:199], v157 offset:16384
	ds_read_b128 v[200:203], v157 offset:17408
	ds_read_b128 v[204:207], v157 offset:18432
	ds_read_b128 v[220:223], v157 offset:19456
	ds_read_b128 v[236:239], v157 offset:20480
	ds_read_b128 v[240:243], v157 offset:21504
	ds_read_b128 v[244:247], v157 offset:22528
	ds_read_b128 v[248:251], v157 offset:23552
	global_load_lds_dwordx4 v134, s[34:35]
	s_add_i32 m0, s57, 0x2000
	s_add_u32 s58, s34, 0x40000
	s_addc_u32 s59, s35, 0
	s_add_i32 s57, s60, s44
	global_load_lds_dwordx4 v130, s[34:35]
	s_mov_b32 m0, s57
	s_nop 0
	global_load_lds_dwordx4 v134, s[58:59]
	s_add_i32 m0, s57, 0x2000
	s_nop 0
	global_load_lds_dwordx4 v130, s[58:59]
	s_mov_b32 m0, s48
	s_nop 0
	global_load_lds_dwordx4 v136, s[36:37]
	s_mov_b32 m0, s49
	s_nop 0
	global_load_lds_dwordx4 v132, s[36:37]
	s_waitcnt vmcnt(8)
	s_waitcnt lgkmcnt(0)
	s_barrier
	s_waitcnt lgkmcnt(0)
	v_mfma_f32_16x16x32_bf16 v[62:65], v[142:145], v[196:199], v[62:65]
	v_mfma_f32_16x16x32_bf16 v[54:57], v[172:175], v[196:199], v[54:57]
	v_mfma_f32_16x16x32_bf16 v[46:49], v[142:145], v[204:207], v[46:49]
	v_mfma_f32_16x16x32_bf16 v[38:41], v[172:175], v[204:207], v[38:41]
	v_mfma_f32_16x16x32_bf16 v[30:33], v[142:145], v[236:239], v[30:33]
	v_mfma_f32_16x16x32_bf16 v[22:25], v[172:175], v[236:239], v[22:25]
	v_mfma_f32_16x16x32_bf16 v[14:17], v[142:145], v[244:247], v[14:17]
	v_mfma_f32_16x16x32_bf16 v[6:9], v[172:175], v[244:247], v[6:9]
	v_mfma_f32_16x16x32_bf16 v[62:65], v[168:171], v[200:203], v[62:65]
	v_mfma_f32_16x16x32_bf16 v[54:57], v[176:179], v[200:203], v[54:57]
	v_mfma_f32_16x16x32_bf16 v[46:49], v[168:171], v[220:223], v[46:49]
	v_mfma_f32_16x16x32_bf16 v[38:41], v[176:179], v[220:223], v[38:41]
	v_mfma_f32_16x16x32_bf16 v[30:33], v[168:171], v[240:243], v[30:33]
	v_mfma_f32_16x16x32_bf16 v[22:25], v[176:179], v[240:243], v[22:25]
	v_mfma_f32_16x16x32_bf16 v[14:17], v[168:171], v[248:251], v[14:17]
	v_mfma_f32_16x16x32_bf16 v[6:9], v[176:179], v[248:251], v[6:9]
	v_mfma_f32_16x16x32_bf16 v[58:61], v[180:183], v[196:199], v[58:61]
	v_mfma_f32_16x16x32_bf16 v[50:53], v[188:191], v[196:199], v[50:53]
	v_mfma_f32_16x16x32_bf16 v[42:45], v[180:183], v[204:207], v[42:45]
	v_mfma_f32_16x16x32_bf16 v[34:37], v[188:191], v[204:207], v[34:37]
	v_mfma_f32_16x16x32_bf16 v[26:29], v[180:183], v[236:239], v[26:29]
	v_mfma_f32_16x16x32_bf16 v[18:21], v[188:191], v[236:239], v[18:21]
	v_mfma_f32_16x16x32_bf16 v[10:13], v[180:183], v[244:247], v[10:13]
	v_mfma_f32_16x16x32_bf16 v[2:5], v[188:191], v[244:247], v[2:5]
	v_mfma_f32_16x16x32_bf16 v[58:61], v[184:187], v[200:203], v[58:61]
	v_mfma_f32_16x16x32_bf16 v[50:53], v[192:195], v[200:203], v[50:53]
	v_mfma_f32_16x16x32_bf16 v[42:45], v[184:187], v[220:223], v[42:45]
	v_mfma_f32_16x16x32_bf16 v[34:37], v[192:195], v[220:223], v[34:37]
	v_mfma_f32_16x16x32_bf16 v[26:29], v[184:187], v[240:243], v[26:29]
	v_mfma_f32_16x16x32_bf16 v[18:21], v[192:195], v[240:243], v[18:21]
	v_mfma_f32_16x16x32_bf16 v[10:13], v[184:187], v[248:251], v[10:13]
	v_mfma_f32_16x16x32_bf16 v[2:5], v[192:195], v[248:251], v[2:5]
	s_barrier
	s_add_i32 s57, 0, 0x18000
	v_add_u32_e32 v164, s57, v155
	s_add_i32 s58, 0, 0x1c000
	ds_read_b128 v[142:145], v164
	ds_read_b128 v[168:171], v164 offset:1024
	ds_read_b128 v[172:175], v164 offset:2048
	ds_read_b128 v[176:179], v164 offset:3072
	v_add_u32_e32 v164, s58, v155
	ds_read_b128 v[180:183], v164
	ds_read_b128 v[184:187], v164 offset:1024
	ds_read_b128 v[188:191], v164 offset:2048
	ds_read_b128 v[192:195], v164 offset:3072
	s_add_u32 s36, s36, 0x40000
	s_addc_u32 s37, s37, 0
	s_mov_b32 m0, s50
	ds_read_b128 v[196:199], v157 offset:32768
	ds_read_b128 v[200:203], v157 offset:33792
	ds_read_b128 v[204:207], v157 offset:34816
	ds_read_b128 v[220:223], v157 offset:35840
	ds_read_b128 v[236:239], v157 offset:36864
	ds_read_b128 v[240:243], v157 offset:37888
	ds_read_b128 v[244:247], v157 offset:38912
	ds_read_b128 v[248:251], v157 offset:39936
	global_load_lds_dwordx4 v136, s[36:37]
	s_mov_b32 m0, s51
	s_nop 0
	global_load_lds_dwordx4 v132, s[36:37]
	s_waitcnt vmcnt(8)
	s_waitcnt lgkmcnt(0)
	s_barrier
	s_waitcnt lgkmcnt(0)
	v_mfma_f32_16x16x32_bf16 v[126:129], v[142:145], v[196:199], v[126:129]
	v_mfma_f32_16x16x32_bf16 v[118:121], v[172:175], v[196:199], v[118:121]
	v_mfma_f32_16x16x32_bf16 v[110:113], v[142:145], v[204:207], v[110:113]
	v_mfma_f32_16x16x32_bf16 v[102:105], v[172:175], v[204:207], v[102:105]
	v_mfma_f32_16x16x32_bf16 v[94:97], v[142:145], v[236:239], v[94:97]
	v_mfma_f32_16x16x32_bf16 v[86:89], v[172:175], v[236:239], v[86:89]
	v_mfma_f32_16x16x32_bf16 v[78:81], v[142:145], v[244:247], v[78:81]
	v_mfma_f32_16x16x32_bf16 v[70:73], v[172:175], v[244:247], v[70:73]
	v_mfma_f32_16x16x32_bf16 v[126:129], v[168:171], v[200:203], v[126:129]
	v_mfma_f32_16x16x32_bf16 v[118:121], v[176:179], v[200:203], v[118:121]
	v_mfma_f32_16x16x32_bf16 v[110:113], v[168:171], v[220:223], v[110:113]
	v_mfma_f32_16x16x32_bf16 v[102:105], v[176:179], v[220:223], v[102:105]
	v_mfma_f32_16x16x32_bf16 v[94:97], v[168:171], v[240:243], v[94:97]
	v_mfma_f32_16x16x32_bf16 v[86:89], v[176:179], v[240:243], v[86:89]
	v_mfma_f32_16x16x32_bf16 v[78:81], v[168:171], v[248:251], v[78:81]
	v_mfma_f32_16x16x32_bf16 v[70:73], v[176:179], v[248:251], v[70:73]
	v_mfma_f32_16x16x32_bf16 v[122:125], v[180:183], v[196:199], v[122:125]
	v_mfma_f32_16x16x32_bf16 v[114:117], v[188:191], v[196:199], v[114:117]
	v_mfma_f32_16x16x32_bf16 v[106:109], v[180:183], v[204:207], v[106:109]
	v_mfma_f32_16x16x32_bf16 v[98:101], v[188:191], v[204:207], v[98:101]
	v_mfma_f32_16x16x32_bf16 v[90:93], v[180:183], v[236:239], v[90:93]
	v_mfma_f32_16x16x32_bf16 v[82:85], v[188:191], v[236:239], v[82:85]
	v_mfma_f32_16x16x32_bf16 v[74:77], v[180:183], v[244:247], v[74:77]
	v_mfma_f32_16x16x32_bf16 v[66:69], v[188:191], v[244:247], v[66:69]
	v_mfma_f32_16x16x32_bf16 v[122:125], v[184:187], v[200:203], v[122:125]
	v_mfma_f32_16x16x32_bf16 v[114:117], v[192:195], v[200:203], v[114:117]
	v_mfma_f32_16x16x32_bf16 v[106:109], v[184:187], v[220:223], v[106:109]
	v_mfma_f32_16x16x32_bf16 v[98:101], v[192:195], v[220:223], v[98:101]
	v_mfma_f32_16x16x32_bf16 v[90:93], v[184:187], v[240:243], v[90:93]
	v_mfma_f32_16x16x32_bf16 v[82:85], v[192:195], v[240:243], v[82:85]
	v_mfma_f32_16x16x32_bf16 v[74:77], v[184:187], v[248:251], v[74:77]
	v_mfma_f32_16x16x32_bf16 v[66:69], v[192:195], v[248:251], v[66:69]
	s_barrier
	s_add_u32 s100, s36, 0xfffc0080
	s_addc_u32 s101, s37, -1
	s_add_i32 s36, s57, s44
	s_add_u32 s34, s34, 0x80
	s_mov_b32 m0, s36
	s_addc_u32 s35, s35, 0
	ds_read_b128 v[196:199], v157 offset:49152
	ds_read_b128 v[200:203], v157 offset:50176
	ds_read_b128 v[204:207], v157 offset:51200
	ds_read_b128 v[220:223], v157 offset:52224
	ds_read_b128 v[236:239], v157 offset:53248
	ds_read_b128 v[240:243], v157 offset:54272
	ds_read_b128 v[244:247], v157 offset:55296
	ds_read_b128 v[248:251], v157 offset:56320
	global_load_lds_dwordx4 v134, s[34:35]
	s_add_i32 m0, s36, 0x2000
	s_add_i32 s36, s58, s44
	global_load_lds_dwordx4 v130, s[34:35]
	s_mov_b32 m0, s36
	s_add_u32 s34, s34, 0x40000
	s_addc_u32 s35, s35, 0
	global_load_lds_dwordx4 v134, s[34:35]
	s_add_i32 m0, s36, 0x2000
	s_nop 0
	global_load_lds_dwordx4 v130, s[34:35]
	s_mov_b32 m0, s52
	s_nop 0
	global_load_lds_dwordx4 v136, s[100:101]
	s_mov_b32 m0, s53
	s_nop 0
	global_load_lds_dwordx4 v132, s[100:101]
	s_waitcnt vmcnt(8)
	s_waitcnt lgkmcnt(0)
	s_barrier
	s_waitcnt lgkmcnt(0)
	v_mfma_f32_16x16x32_bf16 v[62:65], v[142:145], v[196:199], v[62:65]
	v_mfma_f32_16x16x32_bf16 v[54:57], v[172:175], v[196:199], v[54:57]
	v_mfma_f32_16x16x32_bf16 v[46:49], v[142:145], v[204:207], v[46:49]
	v_mfma_f32_16x16x32_bf16 v[38:41], v[172:175], v[204:207], v[38:41]
	v_mfma_f32_16x16x32_bf16 v[30:33], v[142:145], v[236:239], v[30:33]
	v_mfma_f32_16x16x32_bf16 v[22:25], v[172:175], v[236:239], v[22:25]
	v_mfma_f32_16x16x32_bf16 v[14:17], v[142:145], v[244:247], v[14:17]
	v_mfma_f32_16x16x32_bf16 v[6:9], v[172:175], v[244:247], v[6:9]
	v_mfma_f32_16x16x32_bf16 v[62:65], v[168:171], v[200:203], v[62:65]
	v_mfma_f32_16x16x32_bf16 v[54:57], v[176:179], v[200:203], v[54:57]
	v_mfma_f32_16x16x32_bf16 v[46:49], v[168:171], v[220:223], v[46:49]
	v_mfma_f32_16x16x32_bf16 v[38:41], v[176:179], v[220:223], v[38:41]
	v_mfma_f32_16x16x32_bf16 v[30:33], v[168:171], v[240:243], v[30:33]
	v_mfma_f32_16x16x32_bf16 v[22:25], v[176:179], v[240:243], v[22:25]
	v_mfma_f32_16x16x32_bf16 v[14:17], v[168:171], v[248:251], v[14:17]
	v_mfma_f32_16x16x32_bf16 v[6:9], v[176:179], v[248:251], v[6:9]
	v_mfma_f32_16x16x32_bf16 v[58:61], v[180:183], v[196:199], v[58:61]
	v_mfma_f32_16x16x32_bf16 v[50:53], v[188:191], v[196:199], v[50:53]
	v_mfma_f32_16x16x32_bf16 v[42:45], v[180:183], v[204:207], v[42:45]
	v_mfma_f32_16x16x32_bf16 v[34:37], v[188:191], v[204:207], v[34:37]
	v_mfma_f32_16x16x32_bf16 v[26:29], v[180:183], v[236:239], v[26:29]
	v_mfma_f32_16x16x32_bf16 v[18:21], v[188:191], v[236:239], v[18:21]
	v_mfma_f32_16x16x32_bf16 v[10:13], v[180:183], v[244:247], v[10:13]
	v_mfma_f32_16x16x32_bf16 v[2:5], v[188:191], v[244:247], v[2:5]
	v_mfma_f32_16x16x32_bf16 v[58:61], v[184:187], v[200:203], v[58:61]
	v_mfma_f32_16x16x32_bf16 v[50:53], v[192:195], v[200:203], v[50:53]
	v_mfma_f32_16x16x32_bf16 v[42:45], v[184:187], v[220:223], v[42:45]
	v_mfma_f32_16x16x32_bf16 v[34:37], v[192:195], v[220:223], v[34:37]
	v_mfma_f32_16x16x32_bf16 v[26:29], v[184:187], v[240:243], v[26:29]
	v_mfma_f32_16x16x32_bf16 v[18:21], v[192:195], v[240:243], v[18:21]
	v_mfma_f32_16x16x32_bf16 v[10:13], v[184:187], v[248:251], v[10:13]
	v_mfma_f32_16x16x32_bf16 v[2:5], v[192:195], v[248:251], v[2:5]
	s_barrier
	s_add_i32 s56, s56, 2
	s_add_u32 s41, s41, 0x100
	s_addc_u32 s43, s43, 0
	s_add_u32 s30, s30, 0x100
	s_addc_u32 s31, s31, 0
	s_cmp_gt_u32 s56, 13
	s_cbranch_scc0 .LBB0_363
	s_and_b64 vcc, exec, s[16:17]
	s_cbranch_vccz .LBB0_366
	s_barrier
